# EpiUp: wait for the epilogue's stores to drain before the next unit's K-loop starts
# speedup vs baseline: 1.0019x; 1.0019x over previous
; #define PG8_BAR __builtin_amdgcn_s_barrier()
; template <class Epi, class Sched, bool ALIGN_EPI = false, bool SP2 = false>
; __device__ __forceinline__ void gemm_phase(PG8_LAS unsigned char* lds, const Gemm g, const Sched& S, const Epi& E) {
;     ...
;         if constexpr (!Epi::AFTER_DRAIN) { E(acc, cur, wr, wc, fr, fq); S.done(cur); }
;         if (!has_next) break;
; #pragma unroll
;         for (int a = 0; a < 2; ++a)
; #pragma unroll
;             for (int b = 0; b < 2; ++b)
; #pragma unroll
;                 for (int m = 0; m < 4; ++m)
; #pragma unroll
;                     for (int n = 0; n < 2; ++n) acc[a][b][m][n] = (f32x4){0.f, 0.f, 0.f, 0.f};
;         cur = nxt; cA = nA; cB = nB; ++ui;
;         if constexpr (ALIGN_EPI) { if (wr == 1) PG8_BAR; }
;     }
.LBB0_814:
	s_waitcnt vmcnt(0)
	s_andn2_b64 vcc, exec, s[58:59]
	s_mov_b64 s[6:7], -1
	s_cbranch_vccnz .LBB0_780
	s_branch .LBB0_817
